# speedup vs baseline: 1.0070x; 1.0070x over previous
; DEVI u16 f2bf(float f) { return (u16)(pack2(f, 0.f) & 0xffffu); }
; DEVI float bf2f(u16 h) { return __uint_as_float(((unsigned)h) << 16); }
; DEVI void lds_barrier() { asm volatile("s_waitcnt lgkmcnt(0)" ::: "memory"); __builtin_amdgcn_s_barrier(); asm volatile("" ::: "memory"); }
; template <int MODE> ...
;     ...
;         const int colt = ewc * 32 + efr;
;         const int colg = pn * 128 + colt;
;         float cw0[2], cw1[2], cw2[2], cbb[2];
; #pragma unroll
;         for (int n = 0; n < 2; ++n) {
;           cw0[n] = aux0[colg + n * 16]; cw1[n] = aux0[DFF + colg + n * 16]; cw2[n] = aux0[2 * DFF + colg + n * 16]; cbb[n] = aux1[colg + n * 16];
;         }
;         const int gbase = (ewr * 64 + efq * 4) * 256 + colt * 2;
; #pragma unroll
;         for (int ai = 0; ai < 2; ++ai)
; #pragma unroll
;           for (int m = 0; m < 4; ++m)
; #pragma unroll
;             for (int n = 0; n < 2; ++n) {
;               *(u16*)(ls + gbase + ((ai * HALF + m * 16 + 0) * 256 + n * 32)) = f2bf(acc[ai][0][m][n][0]);
;               *(u16*)(ls + gbase + ((ai * HALF + m * 16 + 3) * 256 + n * 32)) = f2bf(acc[ai][0][m][n][3]);
;             }
;         lds_barrier();
;         const int hbase = 65536 + (ewr * 64 + efq * 4) * 256 + (((ewc ^ efq) << 2) << 4) + (efr >> 3) * 16 + (efr & 7) * 2;
; #pragma unroll
;         for (int ai = 0; ai < 2; ++ai)
; #pragma unroll
;           for (int m = 0; m < 4; ++m)
; #pragma unroll
;             for (int n = 0; n < 2; ++n) {
;               const int rowb = ai * HALF + ewr * 64 + m * 16 + efq * 4;
;               float gm = rowb > 0 ? bf2f(*(const u16*)(ls + gbase + ((ai * HALF + m * 16 - 1) * 256 + n * 32))) : 0.f;
;               float gp = rowb < 252 ? bf2f(*(const u16*)(ls + gbase + ((ai * HALF + m * 16 + 4) * 256 + n * 32))) : 0.f;
.LBB0_594:
	s_or_b64 exec, exec, s[8:9]
	v_mov_b32_e32 v140, v164
	s_lshl_b32 s66, s34, 7
	v_bfe_u32 v168, v140, 6, 2
	v_and_b32_e32 v128, 15, v140
	v_lshl_or_b32 v169, v168, 5, v128
	v_or_b32_e32 v138, s66, v169
	v_ashrrev_i32_e32 v139, 31, v138
	v_lshlrev_b64 v[130:131], 2, v[138:139]
	v_lshl_add_u64 v[132:133], s[24:25], 0, v[130:131]
	v_add_co_u32_e32 v142, vcc, 0xa000, v132
	v_lshl_add_u64 v[130:131], s[26:27], 0, v[130:131]
	s_nop 0
	v_addc_co_u32_e32 v143, vcc, 0, v133, vcc
	v_add_co_u32_e32 v144, vcc, 0x15000, v132
	v_ashrrev_i32_e32 v141, 8, v140
	s_nop 0
	v_addc_co_u32_e32 v145, vcc, 0, v133, vcc
	global_load_dword v171, v[132:133], off
	global_load_dword v172, v[142:143], off offset:3072
	global_load_dword v173, v[144:145], off offset:2048
	s_nop 0
	global_load_dword v144, v[144:145], off offset:2112
	s_nop 0
	global_load_dword v145, v[142:143], off offset:3136
	global_load_dword v167, v[132:133], off offset:64
	global_load_dword v170, v[130:131], off
	s_nop 0
	global_load_dword v143, v[130:131], off offset:64
	v_bfe_u32 v142, v140, 4, 2
	v_lshlrev_b32_e32 v130, 6, v141
	v_lshl_or_b32 v174, v142, 2, v130
	v_lshlrev_b32_e32 v175, 8, v174
	v_lshl_or_b32 v169, v169, 1, v175
	v_cvt_pk_bf16_f32 v130, v4, s0
	ds_write_b16 v169, v130
	v_cvt_pk_bf16_f32 v130, v7, s0
	ds_write_b16 v169, v130 offset:768
	v_cvt_pk_bf16_f32 v130, v0, s0
	ds_write_b16 v169, v130 offset:32
	v_cvt_pk_bf16_f32 v130, v3, s0
	ds_write_b16 v169, v130 offset:800
	v_cvt_pk_bf16_f32 v130, v124, s0
	ds_write_b16 v169, v130 offset:4096
	v_cvt_pk_bf16_f32 v130, v127, s0
	ds_write_b16 v169, v130 offset:4864
	v_cvt_pk_bf16_f32 v130, v116, s0
	ds_write_b16 v169, v130 offset:4128
	v_cvt_pk_bf16_f32 v130, v119, s0
	ds_write_b16 v169, v130 offset:4896
	v_cvt_pk_bf16_f32 v130, v108, s0
	ds_write_b16 v169, v130 offset:8192
	v_cvt_pk_bf16_f32 v130, v111, s0
	ds_write_b16 v169, v130 offset:8960
	v_cvt_pk_bf16_f32 v130, v100, s0
	ds_write_b16 v169, v130 offset:8224
	v_cvt_pk_bf16_f32 v130, v103, s0
	ds_write_b16 v169, v130 offset:8992
	v_cvt_pk_bf16_f32 v130, v92, s0
	ds_write_b16 v169, v130 offset:12288
	v_cvt_pk_bf16_f32 v130, v95, s0
	ds_write_b16 v169, v130 offset:13056
	v_cvt_pk_bf16_f32 v130, v84, s0
	ds_write_b16 v169, v130 offset:12320
	v_cvt_pk_bf16_f32 v130, v87, s0
	ds_write_b16 v169, v130 offset:13088
	v_cvt_pk_bf16_f32 v130, v76, s0
	ds_write_b16 v169, v130 offset:32768
	v_cvt_pk_bf16_f32 v130, v79, s0
	ds_write_b16 v169, v130 offset:33536
	v_cvt_pk_bf16_f32 v130, v68, s0
	ds_write_b16 v169, v130 offset:32800
	v_cvt_pk_bf16_f32 v130, v71, s0
	ds_write_b16 v169, v130 offset:33568
	v_cvt_pk_bf16_f32 v130, v60, s0
	ds_write_b16 v169, v130 offset:36864
	v_cvt_pk_bf16_f32 v130, v63, s0
	ds_write_b16 v169, v130 offset:37632
	v_cvt_pk_bf16_f32 v130, v52, s0
	ds_write_b16 v169, v130 offset:36896
	v_cvt_pk_bf16_f32 v130, v55, s0
	ds_write_b16 v169, v130 offset:37664
	v_cvt_pk_bf16_f32 v130, v44, s0
	ds_write_b16 v169, v130 offset:40960
	v_cvt_pk_bf16_f32 v130, v47, s0
	ds_write_b16 v169, v130 offset:41728
	v_cvt_pk_bf16_f32 v130, v36, s0
	ds_write_b16 v169, v130 offset:40992
	v_cvt_pk_bf16_f32 v130, v39, s0
	ds_write_b16 v169, v130 offset:41760
	v_cvt_pk_bf16_f32 v130, v20, s0
	ds_write_b16 v169, v130 offset:45056
	v_cvt_pk_bf16_f32 v130, v23, s0
	ds_write_b16 v169, v130 offset:45824
	v_cvt_pk_bf16_f32 v130, v16, s0
	ds_write_b16 v169, v130 offset:45088
	v_cvt_pk_bf16_f32 v130, v19, s0
	ds_write_b16 v169, v130 offset:45856
	s_waitcnt lgkmcnt(0)
	s_barrier
	v_add_u32_e32 v212, 0xffffff00, v169
	v_max_i32_e32 v212, 0, v212
	ds_read_u16 v180, v212
	ds_read_u16 v181, v169 offset:1024
	v_add_u32_e32 v213, 0xffffff20, v169
	v_max_i32_e32 v213, 0, v213
	ds_read_u16 v182, v213
	ds_read_u16 v183, v169 offset:1056
	ds_read_u16 v184, v169 offset:3840
	ds_read_u16 v185, v169 offset:5120
	ds_read_u16 v186, v169 offset:3872
	ds_read_u16 v187, v169 offset:5152
	ds_read_u16 v188, v169 offset:7936
	ds_read_u16 v189, v169 offset:9216
	ds_read_u16 v190, v169 offset:7968
	ds_read_u16 v191, v169 offset:9248
	ds_read_u16 v192, v169 offset:12032
	ds_read_u16 v193, v169 offset:13312
	ds_read_u16 v194, v169 offset:12064
	ds_read_u16 v195, v169 offset:13344
	ds_read_u16 v196, v169 offset:32512
	ds_read_u16 v197, v169 offset:33792
	ds_read_u16 v198, v169 offset:32544
	ds_read_u16 v199, v169 offset:33824
	ds_read_u16 v200, v169 offset:36608
	ds_read_u16 v201, v169 offset:37888
	ds_read_u16 v202, v169 offset:36640
	ds_read_u16 v203, v169 offset:37920
	ds_read_u16 v204, v169 offset:40704
	ds_read_u16 v205, v169 offset:41984
	ds_read_u16 v206, v169 offset:40736
	ds_read_u16 v207, v169 offset:42016
	ds_read_u16 v208, v169 offset:44800
	ds_read_u16 v209, v169 offset:46080
	ds_read_u16 v210, v169 offset:44832
	ds_read_u16 v211, v169 offset:46112
	s_waitcnt lgkmcnt(0)
	v_cmp_lt_i32_e64 s[8:9], 0, v174
	v_mov_b32_e32 v176, 0
	v_mov_b32_e32 v177, 0
	v_lshlrev_b32_e32 v177, 16, v180
	v_cndmask_b32_e64 v177, 0, v177, s[8:9]
	v_cmp_gt_i32_e64 s[10:11], s74, v174
	v_lshlrev_b32_e32 v176, 16, v181
	s_nop 0
	v_cndmask_b32_e64 v176, 0, v176, s[10:11]
	v_xor_b32_e32 v130, v168, v142
	v_lshlrev_b32_e32 v131, 1, v128
	v_lshlrev_b32_e32 v130, 6, v130
	v_and_b32_e32 v131, 16, v131
	v_lshlrev_b32_e32 v132, 1, v140
	v_and_b32_e32 v132, 14, v132
	v_add3_u32 v130, v175, v130, v131
	v_add3_u32 v168, v130, v132, s73
	s_waitcnt vmcnt(0)
; DEVI u16 f2bf(float f) { return (u16)(pack2(f, 0.f) & 0xffffu); }
; DEVI float bf2f(u16 h) { return __uint_as_float(((unsigned)h) << 16); }
; DEVI float siluf(float x) { return x / (1.f + __expf(-x)); }
; template <int MODE> ...
;     ...
;             for (int n = 0; n < 2; ++n) {
;               const int rowb = ai * HALF + ewr * 64 + m * 16 + efq * 4;
;               float gm = rowb > 0 ? bf2f(*(const u16*)(ls + gbase + ((ai * HALF + m * 16 - 1) * 256 + n * 32))) : 0.f;
;               float gp = rowb < 252 ? bf2f(*(const u16*)(ls + gbase + ((ai * HALF + m * 16 + 4) * 256 + n * 32))) : 0.f;
;               float g0 = acc[ai][0][m][n][0], g1 = acc[ai][0][m][n][1], g2 = acc[ai][0][m][n][2], g3 = acc[ai][0][m][n][3];
;               float z0 = cbb[n] + cw0[n] * gm + cw1[n] * g0 + cw2[n] * g1;
;               float z1 = cbb[n] + cw0[n] * g0 + cw1[n] * g1 + cw2[n] * g2;
;               float z2 = cbb[n] + cw0[n] * g1 + cw1[n] * g2 + cw2[n] * g3;
;               float z3 = cbb[n] + cw0[n] * g2 + cw1[n] * g3 + cw2[n] * gp;
;               char* hp = ls + hbase + ((ai * HALF + m * 16) * 256 + n * 32);
;               *(u16*)(hp) = f2bf(siluf(z0) * acc[ai][1][m][n][0]);
;               *(u16*)(hp + 256) = f2bf(siluf(z1) * acc[ai][1][m][n][1]);
;               *(u16*)(hp + 512) = f2bf(siluf(z2) * acc[ai][1][m][n][2]);
;               *(u16*)(hp + 768) = f2bf(siluf(z3) * acc[ai][1][m][n][3]);
;             }
	v_fma_f32 v130, v171, v177, v170
	v_fmac_f32_e32 v130, v4, v172
	v_fmac_f32_e32 v130, v5, v173
	v_mul_f32_e32 v132, 0xbfb8aa3b, v130
	v_exp_f32_e32 v132, v132
	v_fma_f32 v131, v4, v171, v170
	v_fmac_f32_e32 v131, v5, v172
	v_fma_f32 v133, v5, v171, v170
	v_add_f32_e32 v132, 1.0, v132
	v_fmac_f32_e32 v131, v6, v173
	v_fmac_f32_e32 v133, v6, v172
	v_fma_f32 v6, v6, v171, v170
	v_fmac_f32_e32 v133, v7, v173
	v_fmac_f32_e32 v6, v7, v172
	v_fmac_f32_e32 v6, v173, v176
	v_mul_f32_e32 v175, 0xbfb8aa3b, v131
	v_exp_f32_e32 v175, v175
	v_rcp_f32_e32 v7, v132
	s_nop 0
	v_mul_f32_e32 v7, v130, v7
	v_mul_f32_e32 v7, v12, v7
	v_add_f32_e32 v130, 1.0, v175
	v_cvt_pk_bf16_f32 v7, v7, s0
	ds_write_b16 v168, v7
	v_mul_f32_e32 v132, 0xbfb8aa3b, v133
	v_exp_f32_e32 v132, v132
	v_rcp_f32_e32 v7, v130
	s_nop 0
	v_mul_f32_e32 v7, v131, v7
	v_mul_f32_e32 v7, v13, v7
	v_add_f32_e32 v130, 1.0, v132
	v_cvt_pk_bf16_f32 v7, v7, s0
	ds_write_b16 v168, v7 offset:256
	v_mul_f32_e32 v131, 0xbfb8aa3b, v6
	v_exp_f32_e32 v131, v131
	v_rcp_f32_e32 v7, v130
	s_nop 0
	v_mul_f32_e32 v7, v133, v7
	v_mul_f32_e32 v7, v14, v7
	v_add_f32_e32 v13, 1.0, v131
	v_cvt_pk_bf16_f32 v7, v7, s0
	ds_write_b16 v168, v7 offset:512
	v_rcp_f32_e32 v7, v13
	s_nop 0
	v_mul_f32_e32 v6, v6, v7
	v_mul_f32_e32 v6, v15, v6
	v_cvt_pk_bf16_f32 v6, v6, s0
	ds_write_b16 v168, v6 offset:768
	v_mov_b32_e32 v6, 0
	v_mov_b32_e32 v7, 0
	v_lshlrev_b32_e32 v7, 16, v182
	v_cndmask_b32_e64 v7, 0, v7, s[8:9]
	v_lshlrev_b32_e32 v6, 16, v183
	v_cndmask_b32_e64 v6, 0, v6, s[10:11]
	v_fma_f32 v7, v167, v7, v143
	v_fmac_f32_e32 v7, v0, v145
	v_fmac_f32_e32 v7, v1, v144
	v_mul_f32_e32 v14, 0xbfb8aa3b, v7
	v_exp_f32_e32 v14, v14
	v_fma_f32 v13, v0, v167, v143
	v_fmac_f32_e32 v13, v1, v145
	v_fma_f32 v15, v1, v167, v143
	v_add_f32_e32 v14, 1.0, v14
	v_fmac_f32_e32 v13, v2, v144
	v_fmac_f32_e32 v15, v2, v145
	v_fma_f32 v2, v2, v167, v143
	v_fmac_f32_e32 v15, v3, v144
	v_fmac_f32_e32 v2, v3, v145
	v_fmac_f32_e32 v2, v144, v6
	v_mul_f32_e32 v130, 0xbfb8aa3b, v13
	v_exp_f32_e32 v130, v130
	v_rcp_f32_e32 v3, v14
	s_nop 0
	v_mul_f32_e32 v3, v7, v3
	v_mul_f32_e32 v3, v8, v3
	v_add_f32_e32 v6, 1.0, v130
	v_cvt_pk_bf16_f32 v3, v3, s0
	ds_write_b16 v168, v3 offset:32
	v_mul_f32_e32 v7, 0xbfb8aa3b, v15
	v_exp_f32_e32 v7, v7
	v_rcp_f32_e32 v3, v6
	s_nop 0
	v_mul_f32_e32 v3, v13, v3
	v_mul_f32_e32 v3, v9, v3
	v_add_f32_e32 v6, 1.0, v7
	v_cvt_pk_bf16_f32 v3, v3, s0
	ds_write_b16 v168, v3 offset:288
	v_mul_f32_e32 v7, 0xbfb8aa3b, v2
	v_exp_f32_e32 v7, v7
	v_rcp_f32_e32 v3, v6
	s_nop 0
	v_mul_f32_e32 v3, v15, v3
	v_mul_f32_e32 v3, v10, v3
	v_add_f32_e32 v6, 1.0, v7
	v_cvt_pk_bf16_f32 v3, v3, s0
	ds_write_b16 v168, v3 offset:544
	v_cmp_lt_i32_e64 s[8:9], -1, v141
	v_rcp_f32_e32 v3, v6
	s_nop 0
	v_mul_f32_e32 v2, v2, v3
	v_mul_f32_e32 v2, v11, v2
	v_cvt_pk_bf16_f32 v2, v2, s0
	ds_write_b16 v168, v2 offset:800
	v_mov_b32_e32 v2, 0
	v_mov_b32_e32 v3, 0
	v_lshlrev_b32_e32 v3, 16, v184
	v_cndmask_b32_e64 v3, 0, v3, s[8:9]
	v_or_b32_e32 v6, 16, v174
	v_cmp_gt_i32_e64 s[10:11], s74, v6
	v_lshlrev_b32_e32 v2, 16, v185
	s_nop 0
	v_cndmask_b32_e64 v2, 0, v2, s[10:11]
	v_fma_f32 v3, v171, v3, v170
	v_fmac_f32_e32 v3, v124, v172
	v_fmac_f32_e32 v3, v125, v173
	v_mul_f32_e32 v7, 0xbfb8aa3b, v3
	v_exp_f32_e32 v7, v7
	v_fma_f32 v13, v126, v171, v170
	v_fmac_f32_e32 v13, v127, v172
	v_fmac_f32_e32 v13, v173, v2
	v_add_f32_e32 v7, 1.0, v7
	v_fma_f32 v6, v124, v171, v170
	v_fmac_f32_e32 v6, v125, v172
	v_fmac_f32_e32 v6, v126, v173
	v_mul_f32_e32 v10, 0xbfb8aa3b, v6
	v_exp_f32_e32 v10, v10
	v_rcp_f32_e32 v2, v7
	s_nop 0
	v_mul_f32_e32 v2, v3, v2
	v_mul_f32_e32 v2, v120, v2
	v_add_f32_e32 v3, 1.0, v10
	v_cvt_pk_bf16_f32 v2, v2, s0
	ds_write_b16 v168, v2 offset:4096
	v_fma_f32 v9, v125, v171, v170
	v_fmac_f32_e32 v9, v126, v172
	v_fmac_f32_e32 v9, v127, v173
	v_mul_f32_e32 v7, 0xbfb8aa3b, v9
	v_exp_f32_e32 v7, v7
	v_rcp_f32_e32 v2, v3
	s_nop 0
	v_mul_f32_e32 v2, v6, v2
	v_mul_f32_e32 v2, v121, v2
	v_add_f32_e32 v3, 1.0, v7
	v_cvt_pk_bf16_f32 v2, v2, s0
	ds_write_b16 v168, v2 offset:4352
	v_mul_f32_e32 v6, 0xbfb8aa3b, v13
	v_exp_f32_e32 v6, v6
	v_rcp_f32_e32 v2, v3
	s_nop 0
	v_mul_f32_e32 v2, v9, v2
	v_mul_f32_e32 v2, v122, v2
	v_add_f32_e32 v3, 1.0, v6
	v_cvt_pk_bf16_f32 v2, v2, s0
	ds_write_b16 v168, v2 offset:4608
	v_rcp_f32_e32 v2, v3
	s_nop 0
	v_mul_f32_e32 v2, v13, v2
	v_mul_f32_e32 v2, v123, v2
	v_cvt_pk_bf16_f32 v2, v2, s0
	ds_write_b16 v168, v2 offset:4864
	v_mov_b32_e32 v2, 0
	v_mov_b32_e32 v3, 0
	v_lshlrev_b32_e32 v3, 16, v186
	v_cndmask_b32_e64 v3, 0, v3, s[8:9]
	v_lshlrev_b32_e32 v2, 16, v187
	v_cndmask_b32_e64 v2, 0, v2, s[10:11]
	v_fma_f32 v3, v167, v3, v143
	v_fmac_f32_e32 v3, v116, v145
	v_fmac_f32_e32 v3, v117, v144
	v_mul_f32_e32 v7, 0xbfb8aa3b, v3
	v_exp_f32_e32 v7, v7
	v_fma_f32 v13, v118, v167, v143
	v_fmac_f32_e32 v13, v119, v145
	v_fmac_f32_e32 v13, v144, v2
	v_add_f32_e32 v7, 1.0, v7
	v_fma_f32 v6, v116, v167, v143
	v_fmac_f32_e32 v6, v117, v145
	v_fmac_f32_e32 v6, v118, v144
	v_mul_f32_e32 v10, 0xbfb8aa3b, v6
	v_exp_f32_e32 v10, v10
	v_rcp_f32_e32 v2, v7
	s_nop 0
	v_mul_f32_e32 v2, v3, v2
	v_mul_f32_e32 v2, v112, v2
	v_add_f32_e32 v3, 1.0, v10
	v_cvt_pk_bf16_f32 v2, v2, s0
	ds_write_b16 v168, v2 offset:4128
	v_fma_f32 v9, v117, v167, v143
	v_fmac_f32_e32 v9, v118, v145
	v_fmac_f32_e32 v9, v119, v144
	v_mul_f32_e32 v7, 0xbfb8aa3b, v9
	v_exp_f32_e32 v7, v7
	v_rcp_f32_e32 v2, v3
	s_nop 0
	v_mul_f32_e32 v2, v6, v2
	v_mul_f32_e32 v2, v113, v2
	v_add_f32_e32 v3, 1.0, v7
	v_cvt_pk_bf16_f32 v2, v2, s0
	ds_write_b16 v168, v2 offset:4384
	v_mul_f32_e32 v6, 0xbfb8aa3b, v13
	v_exp_f32_e32 v6, v6
	v_rcp_f32_e32 v2, v3
	s_nop 0
	v_mul_f32_e32 v2, v9, v2
; DEVI u16 f2bf(float f) { return (u16)(pack2(f, 0.f) & 0xffffu); }
; DEVI float bf2f(u16 h) { return __uint_as_float(((unsigned)h) << 16); }
; DEVI float siluf(float x) { return x / (1.f + __expf(-x)); }
; template <int MODE> ...
;     ...
;             for (int n = 0; n < 2; ++n) {
;               const int rowb = ai * HALF + ewr * 64 + m * 16 + efq * 4;
;               float gm = rowb > 0 ? bf2f(*(const u16*)(ls + gbase + ((ai * HALF + m * 16 - 1) * 256 + n * 32))) : 0.f;
;               float gp = rowb < 252 ? bf2f(*(const u16*)(ls + gbase + ((ai * HALF + m * 16 + 4) * 256 + n * 32))) : 0.f;
;               float g0 = acc[ai][0][m][n][0], g1 = acc[ai][0][m][n][1], g2 = acc[ai][0][m][n][2], g3 = acc[ai][0][m][n][3];
;               float z0 = cbb[n] + cw0[n] * gm + cw1[n] * g0 + cw2[n] * g1;
;               float z1 = cbb[n] + cw0[n] * g0 + cw1[n] * g1 + cw2[n] * g2;
;               float z2 = cbb[n] + cw0[n] * g1 + cw1[n] * g2 + cw2[n] * g3;
;               float z3 = cbb[n] + cw0[n] * g2 + cw1[n] * g3 + cw2[n] * gp;
;               char* hp = ls + hbase + ((ai * HALF + m * 16) * 256 + n * 32);
;               *(u16*)(hp) = f2bf(siluf(z0) * acc[ai][1][m][n][0]);
;               *(u16*)(hp + 256) = f2bf(siluf(z1) * acc[ai][1][m][n][1]);
;               *(u16*)(hp + 512) = f2bf(siluf(z2) * acc[ai][1][m][n][2]);
;               *(u16*)(hp + 768) = f2bf(siluf(z3) * acc[ai][1][m][n][3]);
;             }
	v_mul_f32_e32 v2, v114, v2
	v_add_f32_e32 v3, 1.0, v6
	v_cvt_pk_bf16_f32 v2, v2, s0
	ds_write_b16 v168, v2 offset:4640
	v_rcp_f32_e32 v2, v3
	s_nop 0
	v_mul_f32_e32 v2, v13, v2
	v_mul_f32_e32 v2, v115, v2
	v_cvt_pk_bf16_f32 v2, v2, s0
	ds_write_b16 v168, v2 offset:4896
	v_mov_b32_e32 v2, 0
	v_mov_b32_e32 v3, 0
	v_lshlrev_b32_e32 v3, 16, v188
	v_cndmask_b32_e64 v3, 0, v3, s[8:9]
	v_or_b32_e32 v6, 32, v174
	v_cmp_gt_i32_e64 s[10:11], s74, v6
	v_lshlrev_b32_e32 v2, 16, v189
	s_nop 0
	v_cndmask_b32_e64 v2, 0, v2, s[10:11]
	v_fma_f32 v3, v171, v3, v170
	v_fmac_f32_e32 v3, v108, v172
	v_fmac_f32_e32 v3, v109, v173
	v_mul_f32_e32 v7, 0xbfb8aa3b, v3
	v_exp_f32_e32 v7, v7
	v_fma_f32 v13, v110, v171, v170
	v_fmac_f32_e32 v13, v111, v172
	v_fmac_f32_e32 v13, v173, v2
	v_add_f32_e32 v7, 1.0, v7
	v_fma_f32 v6, v108, v171, v170
	v_fmac_f32_e32 v6, v109, v172
	v_fmac_f32_e32 v6, v110, v173
	v_mul_f32_e32 v10, 0xbfb8aa3b, v6
	v_exp_f32_e32 v10, v10
	v_rcp_f32_e32 v2, v7
	s_nop 0
	v_mul_f32_e32 v2, v3, v2
	v_mul_f32_e32 v2, v104, v2
	v_add_f32_e32 v3, 1.0, v10
	v_cvt_pk_bf16_f32 v2, v2, s0
	ds_write_b16 v168, v2 offset:8192
	v_fma_f32 v9, v109, v171, v170
	v_fmac_f32_e32 v9, v110, v172
	v_fmac_f32_e32 v9, v111, v173
	v_mul_f32_e32 v7, 0xbfb8aa3b, v9
	v_exp_f32_e32 v7, v7
	v_rcp_f32_e32 v2, v3
	s_nop 0
	v_mul_f32_e32 v2, v6, v2
	v_mul_f32_e32 v2, v105, v2
	v_add_f32_e32 v3, 1.0, v7
	v_cvt_pk_bf16_f32 v2, v2, s0
	ds_write_b16 v168, v2 offset:8448
	v_mul_f32_e32 v6, 0xbfb8aa3b, v13
	v_exp_f32_e32 v6, v6
	v_rcp_f32_e32 v2, v3
	s_nop 0
	v_mul_f32_e32 v2, v9, v2
	v_mul_f32_e32 v2, v106, v2
	v_add_f32_e32 v3, 1.0, v6
	v_cvt_pk_bf16_f32 v2, v2, s0
	ds_write_b16 v168, v2 offset:8704
	v_rcp_f32_e32 v2, v3
	s_nop 0
	v_mul_f32_e32 v2, v13, v2
	v_mul_f32_e32 v2, v107, v2
	v_cvt_pk_bf16_f32 v2, v2, s0
	ds_write_b16 v168, v2 offset:8960
	v_mov_b32_e32 v2, 0
	v_mov_b32_e32 v3, 0
	v_lshlrev_b32_e32 v3, 16, v190
	v_cndmask_b32_e64 v3, 0, v3, s[8:9]
	v_lshlrev_b32_e32 v2, 16, v191
	v_cndmask_b32_e64 v2, 0, v2, s[10:11]
	v_fma_f32 v3, v167, v3, v143
	v_fmac_f32_e32 v3, v100, v145
	v_fmac_f32_e32 v3, v101, v144
	v_mul_f32_e32 v7, 0xbfb8aa3b, v3
	v_exp_f32_e32 v7, v7
	v_fma_f32 v13, v102, v167, v143
	v_fmac_f32_e32 v13, v103, v145
	v_fmac_f32_e32 v13, v144, v2
	v_add_f32_e32 v7, 1.0, v7
	v_fma_f32 v6, v100, v167, v143
	v_fmac_f32_e32 v6, v101, v145
	v_fmac_f32_e32 v6, v102, v144
	v_mul_f32_e32 v10, 0xbfb8aa3b, v6
	v_exp_f32_e32 v10, v10
	v_rcp_f32_e32 v2, v7
	s_nop 0
	v_mul_f32_e32 v2, v3, v2
	v_mul_f32_e32 v2, v96, v2
	v_add_f32_e32 v3, 1.0, v10
	v_cvt_pk_bf16_f32 v2, v2, s0
	ds_write_b16 v168, v2 offset:8224
	v_fma_f32 v9, v101, v167, v143
	v_fmac_f32_e32 v9, v102, v145
	v_fmac_f32_e32 v9, v103, v144
	v_mul_f32_e32 v7, 0xbfb8aa3b, v9
	v_exp_f32_e32 v7, v7
	v_rcp_f32_e32 v2, v3
	s_nop 0
	v_mul_f32_e32 v2, v6, v2
	v_mul_f32_e32 v2, v97, v2
	v_add_f32_e32 v3, 1.0, v7
	v_cvt_pk_bf16_f32 v2, v2, s0
	ds_write_b16 v168, v2 offset:8480
	v_mul_f32_e32 v6, 0xbfb8aa3b, v13
	v_exp_f32_e32 v6, v6
	v_rcp_f32_e32 v2, v3
	s_nop 0
	v_mul_f32_e32 v2, v9, v2
	v_mul_f32_e32 v2, v98, v2
	v_add_f32_e32 v3, 1.0, v6
	v_cvt_pk_bf16_f32 v2, v2, s0
	ds_write_b16 v168, v2 offset:8736
	v_rcp_f32_e32 v2, v3
	s_nop 0
	v_mul_f32_e32 v2, v13, v2
	v_mul_f32_e32 v2, v99, v2
	v_cvt_pk_bf16_f32 v2, v2, s0
	ds_write_b16 v168, v2 offset:8992
	v_mov_b32_e32 v2, 0
	v_mov_b32_e32 v3, 0
	v_lshlrev_b32_e32 v3, 16, v192
	v_cndmask_b32_e64 v3, 0, v3, s[8:9]
	v_or_b32_e32 v6, 48, v174
	v_cmp_gt_i32_e64 s[10:11], s74, v6
	v_lshlrev_b32_e32 v2, 16, v193
	s_nop 0
	v_cndmask_b32_e64 v2, 0, v2, s[10:11]
	v_fma_f32 v3, v171, v3, v170
	v_fmac_f32_e32 v3, v92, v172
	v_fmac_f32_e32 v3, v93, v173
	v_mul_f32_e32 v7, 0xbfb8aa3b, v3
	v_exp_f32_e32 v7, v7
	v_fma_f32 v13, v94, v171, v170
	v_fmac_f32_e32 v13, v95, v172
	v_fmac_f32_e32 v13, v173, v2
	v_add_f32_e32 v7, 1.0, v7
	v_fma_f32 v6, v92, v171, v170
	v_fmac_f32_e32 v6, v93, v172
	v_fmac_f32_e32 v6, v94, v173
	v_mul_f32_e32 v10, 0xbfb8aa3b, v6
	v_exp_f32_e32 v10, v10
	v_rcp_f32_e32 v2, v7
	s_nop 0
	v_mul_f32_e32 v2, v3, v2
	v_mul_f32_e32 v2, v88, v2
	v_add_f32_e32 v3, 1.0, v10
	v_cvt_pk_bf16_f32 v2, v2, s0
	ds_write_b16 v168, v2 offset:12288
	v_fma_f32 v9, v93, v171, v170
	v_fmac_f32_e32 v9, v94, v172
	v_fmac_f32_e32 v9, v95, v173
	v_mul_f32_e32 v7, 0xbfb8aa3b, v9
	v_exp_f32_e32 v7, v7
	v_rcp_f32_e32 v2, v3
	s_nop 0
	v_mul_f32_e32 v2, v6, v2
	v_mul_f32_e32 v2, v89, v2
	v_add_f32_e32 v3, 1.0, v7
	v_cvt_pk_bf16_f32 v2, v2, s0
	ds_write_b16 v168, v2 offset:12544
	v_mul_f32_e32 v6, 0xbfb8aa3b, v13
	v_exp_f32_e32 v6, v6
	v_rcp_f32_e32 v2, v3
	s_nop 0
	v_mul_f32_e32 v2, v9, v2
	v_mul_f32_e32 v2, v90, v2
	v_add_f32_e32 v3, 1.0, v6
	v_cvt_pk_bf16_f32 v2, v2, s0
	ds_write_b16 v168, v2 offset:12800
	v_rcp_f32_e32 v2, v3
	s_nop 0
	v_mul_f32_e32 v2, v13, v2
	v_mul_f32_e32 v2, v91, v2
	v_cvt_pk_bf16_f32 v2, v2, s0
	ds_write_b16 v168, v2 offset:13056
	v_mov_b32_e32 v2, 0
	v_mov_b32_e32 v3, 0
	v_lshlrev_b32_e32 v3, 16, v194
	v_cndmask_b32_e64 v3, 0, v3, s[8:9]
	v_lshlrev_b32_e32 v2, 16, v195
	v_cndmask_b32_e64 v2, 0, v2, s[10:11]
	v_fma_f32 v3, v167, v3, v143
	v_fmac_f32_e32 v3, v84, v145
	v_fmac_f32_e32 v3, v85, v144
	v_mul_f32_e32 v7, 0xbfb8aa3b, v3
	v_exp_f32_e32 v7, v7
	v_fma_f32 v13, v86, v167, v143
	v_fmac_f32_e32 v13, v87, v145
	v_fmac_f32_e32 v13, v144, v2
	v_add_f32_e32 v7, 1.0, v7
	v_fma_f32 v6, v84, v167, v143
	v_fmac_f32_e32 v6, v85, v145
	v_fmac_f32_e32 v6, v86, v144
	v_mul_f32_e32 v10, 0xbfb8aa3b, v6
	v_exp_f32_e32 v10, v10
	v_rcp_f32_e32 v2, v7
	s_nop 0
	v_mul_f32_e32 v2, v3, v2
	v_mul_f32_e32 v2, v80, v2
	v_add_f32_e32 v3, 1.0, v10
	v_cvt_pk_bf16_f32 v2, v2, s0
; DEVI u16 f2bf(float f) { return (u16)(pack2(f, 0.f) & 0xffffu); }
; DEVI float bf2f(u16 h) { return __uint_as_float(((unsigned)h) << 16); }
; DEVI float siluf(float x) { return x / (1.f + __expf(-x)); }
; template <int MODE> ...
;     ...
;             for (int n = 0; n < 2; ++n) {
;               const int rowb = ai * HALF + ewr * 64 + m * 16 + efq * 4;
;               float gm = rowb > 0 ? bf2f(*(const u16*)(ls + gbase + ((ai * HALF + m * 16 - 1) * 256 + n * 32))) : 0.f;
;               float gp = rowb < 252 ? bf2f(*(const u16*)(ls + gbase + ((ai * HALF + m * 16 + 4) * 256 + n * 32))) : 0.f;
;               float g0 = acc[ai][0][m][n][0], g1 = acc[ai][0][m][n][1], g2 = acc[ai][0][m][n][2], g3 = acc[ai][0][m][n][3];
;               float z0 = cbb[n] + cw0[n] * gm + cw1[n] * g0 + cw2[n] * g1;
;               float z1 = cbb[n] + cw0[n] * g0 + cw1[n] * g1 + cw2[n] * g2;
;               float z2 = cbb[n] + cw0[n] * g1 + cw1[n] * g2 + cw2[n] * g3;
;               float z3 = cbb[n] + cw0[n] * g2 + cw1[n] * g3 + cw2[n] * gp;
;               char* hp = ls + hbase + ((ai * HALF + m * 16) * 256 + n * 32);
;               *(u16*)(hp) = f2bf(siluf(z0) * acc[ai][1][m][n][0]);
;               *(u16*)(hp + 256) = f2bf(siluf(z1) * acc[ai][1][m][n][1]);
;               *(u16*)(hp + 512) = f2bf(siluf(z2) * acc[ai][1][m][n][2]);
;               *(u16*)(hp + 768) = f2bf(siluf(z3) * acc[ai][1][m][n][3]);
;             }
	ds_write_b16 v168, v2 offset:12320
	v_fma_f32 v9, v85, v167, v143
	v_fmac_f32_e32 v9, v86, v145
	v_fmac_f32_e32 v9, v87, v144
	v_mul_f32_e32 v7, 0xbfb8aa3b, v9
	v_exp_f32_e32 v7, v7
	v_rcp_f32_e32 v2, v3
	s_nop 0
	v_mul_f32_e32 v2, v6, v2
	v_mul_f32_e32 v2, v81, v2
	v_add_f32_e32 v3, 1.0, v7
	v_cvt_pk_bf16_f32 v2, v2, s0
	ds_write_b16 v168, v2 offset:12576
	v_mul_f32_e32 v6, 0xbfb8aa3b, v13
	v_exp_f32_e32 v6, v6
	v_rcp_f32_e32 v2, v3
	s_nop 0
	v_mul_f32_e32 v2, v9, v2
	v_mul_f32_e32 v2, v82, v2
	v_add_f32_e32 v3, 1.0, v6
	v_cvt_pk_bf16_f32 v2, v2, s0
	ds_write_b16 v168, v2 offset:12832
	v_cmp_lt_i32_e64 s[8:9], s75, v174
	v_rcp_f32_e32 v2, v3
	s_nop 0
	v_mul_f32_e32 v2, v13, v2
	v_mul_f32_e32 v2, v83, v2
	v_cvt_pk_bf16_f32 v2, v2, s0
	ds_write_b16 v168, v2 offset:13088
	v_mov_b32_e32 v2, 0
	v_mov_b32_e32 v3, 0
	v_lshlrev_b32_e32 v3, 16, v196
	v_cndmask_b32_e64 v3, 0, v3, s[8:9]
	v_cmp_gt_i32_e64 s[10:11], s76, v174
	v_lshlrev_b32_e32 v2, 16, v197
	s_nop 0
	v_cndmask_b32_e64 v2, 0, v2, s[10:11]
	v_fma_f32 v3, v171, v3, v170
	v_fmac_f32_e32 v3, v76, v172
	v_fmac_f32_e32 v3, v77, v173
	v_mul_f32_e32 v7, 0xbfb8aa3b, v3
	v_exp_f32_e32 v7, v7
	v_fma_f32 v13, v78, v171, v170
	v_fmac_f32_e32 v13, v79, v172
	v_fmac_f32_e32 v13, v173, v2
	v_add_f32_e32 v7, 1.0, v7
	v_fma_f32 v6, v76, v171, v170
	v_fmac_f32_e32 v6, v77, v172
	v_fmac_f32_e32 v6, v78, v173
	v_mul_f32_e32 v10, 0xbfb8aa3b, v6
	v_exp_f32_e32 v10, v10
	v_rcp_f32_e32 v2, v7
	s_nop 0
	v_mul_f32_e32 v2, v3, v2
	v_mul_f32_e32 v2, v72, v2
	v_add_f32_e32 v3, 1.0, v10
	v_cvt_pk_bf16_f32 v2, v2, s0
	ds_write_b16 v168, v2 offset:32768
	v_fma_f32 v9, v77, v171, v170
	v_fmac_f32_e32 v9, v78, v172
	v_fmac_f32_e32 v9, v79, v173
	v_mul_f32_e32 v7, 0xbfb8aa3b, v9
	v_exp_f32_e32 v7, v7
	v_rcp_f32_e32 v2, v3
	s_nop 0
	v_mul_f32_e32 v2, v6, v2
	v_mul_f32_e32 v2, v73, v2
	v_add_f32_e32 v3, 1.0, v7
	v_cvt_pk_bf16_f32 v2, v2, s0
	ds_write_b16 v168, v2 offset:33024
	v_mul_f32_e32 v6, 0xbfb8aa3b, v13
	v_exp_f32_e32 v6, v6
	v_rcp_f32_e32 v2, v3
	s_nop 0
	v_mul_f32_e32 v2, v9, v2
	v_mul_f32_e32 v2, v74, v2
	v_add_f32_e32 v3, 1.0, v6
	v_cvt_pk_bf16_f32 v2, v2, s0
	ds_write_b16 v168, v2 offset:33280
	v_rcp_f32_e32 v2, v3
	s_nop 0
	v_mul_f32_e32 v2, v13, v2
	v_mul_f32_e32 v2, v75, v2
	v_cvt_pk_bf16_f32 v2, v2, s0
	ds_write_b16 v168, v2 offset:33536
	v_mov_b32_e32 v2, 0
	v_mov_b32_e32 v3, 0
	v_lshlrev_b32_e32 v3, 16, v198
	v_cndmask_b32_e64 v3, 0, v3, s[8:9]
	v_lshlrev_b32_e32 v2, 16, v199
	v_cndmask_b32_e64 v2, 0, v2, s[10:11]
	v_fma_f32 v3, v167, v3, v143
	v_fmac_f32_e32 v3, v68, v145
	v_fmac_f32_e32 v3, v69, v144
	v_mul_f32_e32 v7, 0xbfb8aa3b, v3
	v_exp_f32_e32 v7, v7
	v_fma_f32 v13, v70, v167, v143
	v_fmac_f32_e32 v13, v71, v145
	v_fmac_f32_e32 v13, v144, v2
	v_add_f32_e32 v7, 1.0, v7
	v_fma_f32 v6, v68, v167, v143
	v_fmac_f32_e32 v6, v69, v145
	v_fmac_f32_e32 v6, v70, v144
	v_mul_f32_e32 v10, 0xbfb8aa3b, v6
	v_exp_f32_e32 v10, v10
	v_rcp_f32_e32 v2, v7
	s_nop 0
	v_mul_f32_e32 v2, v3, v2
	v_mul_f32_e32 v2, v64, v2
	v_add_f32_e32 v3, 1.0, v10
	v_cvt_pk_bf16_f32 v2, v2, s0
	ds_write_b16 v168, v2 offset:32800
	v_fma_f32 v9, v69, v167, v143
	v_fmac_f32_e32 v9, v70, v145
	v_fmac_f32_e32 v9, v71, v144
	v_mul_f32_e32 v7, 0xbfb8aa3b, v9
	v_exp_f32_e32 v7, v7
	v_rcp_f32_e32 v2, v3
	s_nop 0
	v_mul_f32_e32 v2, v6, v2
	v_mul_f32_e32 v2, v65, v2
	v_add_f32_e32 v3, 1.0, v7
	v_cvt_pk_bf16_f32 v2, v2, s0
	ds_write_b16 v168, v2 offset:33056
	v_mul_f32_e32 v6, 0xbfb8aa3b, v13
	v_exp_f32_e32 v6, v6
	v_rcp_f32_e32 v2, v3
	s_nop 0
	v_mul_f32_e32 v2, v9, v2
	v_mul_f32_e32 v2, v66, v2
	v_add_f32_e32 v3, 1.0, v6
	v_cvt_pk_bf16_f32 v2, v2, s0
	ds_write_b16 v168, v2 offset:33312
	v_cmp_lt_i32_e64 s[8:9], s77, v174
	v_rcp_f32_e32 v2, v3
	s_nop 0
	v_mul_f32_e32 v2, v13, v2
	v_mul_f32_e32 v2, v67, v2
	v_cvt_pk_bf16_f32 v2, v2, s0
	ds_write_b16 v168, v2 offset:33568
	v_mov_b32_e32 v2, 0
	v_mov_b32_e32 v3, 0
	v_lshlrev_b32_e32 v3, 16, v200
	v_cndmask_b32_e64 v3, 0, v3, s[8:9]
	v_cmp_gt_i32_e64 s[10:11], s78, v174
	v_lshlrev_b32_e32 v2, 16, v201
	s_nop 0
	v_cndmask_b32_e64 v2, 0, v2, s[10:11]
	v_fma_f32 v3, v171, v3, v170
	v_fmac_f32_e32 v3, v60, v172
	v_fmac_f32_e32 v3, v61, v173
	v_mul_f32_e32 v7, 0xbfb8aa3b, v3
	v_exp_f32_e32 v7, v7
	v_fma_f32 v13, v62, v171, v170
	v_fmac_f32_e32 v13, v63, v172
	v_fmac_f32_e32 v13, v173, v2
	v_add_f32_e32 v7, 1.0, v7
	v_fma_f32 v6, v60, v171, v170
	v_fmac_f32_e32 v6, v61, v172
	v_fmac_f32_e32 v6, v62, v173
	v_mul_f32_e32 v10, 0xbfb8aa3b, v6
	v_exp_f32_e32 v10, v10
	v_rcp_f32_e32 v2, v7
	s_nop 0
	v_mul_f32_e32 v2, v3, v2
	v_mul_f32_e32 v2, v56, v2
	v_add_f32_e32 v3, 1.0, v10
	v_cvt_pk_bf16_f32 v2, v2, s0
	ds_write_b16 v168, v2 offset:36864
	v_fma_f32 v9, v61, v171, v170
	v_fmac_f32_e32 v9, v62, v172
	v_fmac_f32_e32 v9, v63, v173
	v_mul_f32_e32 v7, 0xbfb8aa3b, v9
	v_exp_f32_e32 v7, v7
	v_rcp_f32_e32 v2, v3
	s_nop 0
	v_mul_f32_e32 v2, v6, v2
	v_mul_f32_e32 v2, v57, v2
	v_add_f32_e32 v3, 1.0, v7
	v_cvt_pk_bf16_f32 v2, v2, s0
	ds_write_b16 v168, v2 offset:37120
	v_mul_f32_e32 v6, 0xbfb8aa3b, v13
	v_exp_f32_e32 v6, v6
	v_rcp_f32_e32 v2, v3
	s_nop 0
	v_mul_f32_e32 v2, v9, v2
	v_mul_f32_e32 v2, v58, v2
	v_add_f32_e32 v3, 1.0, v6
	v_cvt_pk_bf16_f32 v2, v2, s0
	ds_write_b16 v168, v2 offset:37376
	v_rcp_f32_e32 v2, v3
	s_nop 0
	v_mul_f32_e32 v2, v13, v2
	v_mul_f32_e32 v2, v59, v2
	v_cvt_pk_bf16_f32 v2, v2, s0
	ds_write_b16 v168, v2 offset:37632
	v_mov_b32_e32 v2, 0
	v_mov_b32_e32 v3, 0
	v_lshlrev_b32_e32 v3, 16, v202
	v_cndmask_b32_e64 v3, 0, v3, s[8:9]
	v_lshlrev_b32_e32 v2, 16, v203
	v_cndmask_b32_e64 v2, 0, v2, s[10:11]
	v_fma_f32 v3, v167, v3, v143
	v_fmac_f32_e32 v3, v52, v145
	v_fmac_f32_e32 v3, v53, v144
; DEVI u16 f2bf(float f) { return (u16)(pack2(f, 0.f) & 0xffffu); }
; DEVI float bf2f(u16 h) { return __uint_as_float(((unsigned)h) << 16); }
; DEVI float siluf(float x) { return x / (1.f + __expf(-x)); }
; template <int MODE> ...
;     ...
;             for (int n = 0; n < 2; ++n) {
;               const int rowb = ai * HALF + ewr * 64 + m * 16 + efq * 4;
;               float gm = rowb > 0 ? bf2f(*(const u16*)(ls + gbase + ((ai * HALF + m * 16 - 1) * 256 + n * 32))) : 0.f;
;               float gp = rowb < 252 ? bf2f(*(const u16*)(ls + gbase + ((ai * HALF + m * 16 + 4) * 256 + n * 32))) : 0.f;
;               float g0 = acc[ai][0][m][n][0], g1 = acc[ai][0][m][n][1], g2 = acc[ai][0][m][n][2], g3 = acc[ai][0][m][n][3];
;               float z0 = cbb[n] + cw0[n] * gm + cw1[n] * g0 + cw2[n] * g1;
;               float z1 = cbb[n] + cw0[n] * g0 + cw1[n] * g1 + cw2[n] * g2;
;               float z2 = cbb[n] + cw0[n] * g1 + cw1[n] * g2 + cw2[n] * g3;
;               float z3 = cbb[n] + cw0[n] * g2 + cw1[n] * g3 + cw2[n] * gp;
;               char* hp = ls + hbase + ((ai * HALF + m * 16) * 256 + n * 32);
;               *(u16*)(hp) = f2bf(siluf(z0) * acc[ai][1][m][n][0]);
;               *(u16*)(hp + 256) = f2bf(siluf(z1) * acc[ai][1][m][n][1]);
;               *(u16*)(hp + 512) = f2bf(siluf(z2) * acc[ai][1][m][n][2]);
;               *(u16*)(hp + 768) = f2bf(siluf(z3) * acc[ai][1][m][n][3]);
;             }
	v_mul_f32_e32 v7, 0xbfb8aa3b, v3
	v_exp_f32_e32 v7, v7
	v_fma_f32 v13, v54, v167, v143
	v_fmac_f32_e32 v13, v55, v145
	v_fmac_f32_e32 v13, v144, v2
	v_add_f32_e32 v7, 1.0, v7
	v_fma_f32 v6, v52, v167, v143
	v_fmac_f32_e32 v6, v53, v145
	v_fmac_f32_e32 v6, v54, v144
	v_mul_f32_e32 v10, 0xbfb8aa3b, v6
	v_exp_f32_e32 v10, v10
	v_rcp_f32_e32 v2, v7
	s_nop 0
	v_mul_f32_e32 v2, v3, v2
	v_mul_f32_e32 v2, v48, v2
	v_add_f32_e32 v3, 1.0, v10
	v_cvt_pk_bf16_f32 v2, v2, s0
	ds_write_b16 v168, v2 offset:36896
	v_fma_f32 v9, v53, v167, v143
	v_fmac_f32_e32 v9, v54, v145
	v_fmac_f32_e32 v9, v55, v144
	v_mul_f32_e32 v7, 0xbfb8aa3b, v9
	v_exp_f32_e32 v7, v7
	v_rcp_f32_e32 v2, v3
	s_nop 0
	v_mul_f32_e32 v2, v6, v2
	v_mul_f32_e32 v2, v49, v2
	v_add_f32_e32 v3, 1.0, v7
	v_cvt_pk_bf16_f32 v2, v2, s0
	ds_write_b16 v168, v2 offset:37152
	v_mul_f32_e32 v6, 0xbfb8aa3b, v13
	v_exp_f32_e32 v6, v6
	v_rcp_f32_e32 v2, v3
	s_nop 0
	v_mul_f32_e32 v2, v9, v2
	v_mul_f32_e32 v2, v50, v2
	v_add_f32_e32 v3, 1.0, v6
	v_cvt_pk_bf16_f32 v2, v2, s0
	ds_write_b16 v168, v2 offset:37408
	v_cmp_lt_i32_e64 s[8:9], s79, v174
	v_rcp_f32_e32 v2, v3
	s_nop 0
	v_mul_f32_e32 v2, v13, v2
	v_mul_f32_e32 v2, v51, v2
	v_cvt_pk_bf16_f32 v2, v2, s0
	ds_write_b16 v168, v2 offset:37664
	v_mov_b32_e32 v2, 0
	v_mov_b32_e32 v3, 0
	v_lshlrev_b32_e32 v3, 16, v204
	v_cndmask_b32_e64 v3, 0, v3, s[8:9]
	v_cmp_gt_i32_e64 s[10:11], s81, v174
	v_lshlrev_b32_e32 v2, 16, v205
	s_nop 0
	v_cndmask_b32_e64 v2, 0, v2, s[10:11]
	v_fma_f32 v3, v171, v3, v170
	v_fmac_f32_e32 v3, v44, v172
	v_fmac_f32_e32 v3, v45, v173
	v_mul_f32_e32 v7, 0xbfb8aa3b, v3
	v_exp_f32_e32 v7, v7
	v_fma_f32 v13, v46, v171, v170
	v_fmac_f32_e32 v13, v47, v172
	v_fmac_f32_e32 v13, v173, v2
	v_add_f32_e32 v7, 1.0, v7
	v_fma_f32 v6, v44, v171, v170
	v_fmac_f32_e32 v6, v45, v172
	v_fmac_f32_e32 v6, v46, v173
	v_mul_f32_e32 v10, 0xbfb8aa3b, v6
	v_exp_f32_e32 v10, v10
	v_rcp_f32_e32 v2, v7
	s_nop 0
	v_mul_f32_e32 v2, v3, v2
	v_mul_f32_e32 v2, v40, v2
	v_add_f32_e32 v3, 1.0, v10
	v_cvt_pk_bf16_f32 v2, v2, s0
	ds_write_b16 v168, v2 offset:40960
	v_fma_f32 v9, v45, v171, v170
	v_fmac_f32_e32 v9, v46, v172
	v_fmac_f32_e32 v9, v47, v173
	v_mul_f32_e32 v7, 0xbfb8aa3b, v9
	v_exp_f32_e32 v7, v7
	v_rcp_f32_e32 v2, v3
	s_nop 0
	v_mul_f32_e32 v2, v6, v2
	v_mul_f32_e32 v2, v41, v2
	v_add_f32_e32 v3, 1.0, v7
	v_cvt_pk_bf16_f32 v2, v2, s0
	ds_write_b16 v168, v2 offset:41216
	v_mul_f32_e32 v6, 0xbfb8aa3b, v13
	v_exp_f32_e32 v6, v6
	v_rcp_f32_e32 v2, v3
	s_nop 0
	v_mul_f32_e32 v2, v9, v2
	v_mul_f32_e32 v2, v42, v2
	v_add_f32_e32 v3, 1.0, v6
	v_cvt_pk_bf16_f32 v2, v2, s0
	ds_write_b16 v168, v2 offset:41472
	v_rcp_f32_e32 v2, v3
	s_nop 0
	v_mul_f32_e32 v2, v13, v2
	v_mul_f32_e32 v2, v43, v2
	v_cvt_pk_bf16_f32 v2, v2, s0
	ds_write_b16 v168, v2 offset:41728
	v_mov_b32_e32 v2, 0
	v_mov_b32_e32 v3, 0
	v_lshlrev_b32_e32 v3, 16, v206
	v_cndmask_b32_e64 v3, 0, v3, s[8:9]
	v_lshlrev_b32_e32 v2, 16, v207
	v_cndmask_b32_e64 v2, 0, v2, s[10:11]
	v_fma_f32 v3, v167, v3, v143
	v_fmac_f32_e32 v3, v36, v145
	v_fmac_f32_e32 v3, v37, v144
	v_mul_f32_e32 v7, 0xbfb8aa3b, v3
	v_exp_f32_e32 v7, v7
	v_fma_f32 v13, v38, v167, v143
	v_fmac_f32_e32 v13, v39, v145
	v_fmac_f32_e32 v13, v144, v2
	v_add_f32_e32 v7, 1.0, v7
	v_fma_f32 v6, v36, v167, v143
	v_fmac_f32_e32 v6, v37, v145
	v_fmac_f32_e32 v6, v38, v144
	v_mul_f32_e32 v10, 0xbfb8aa3b, v6
	v_exp_f32_e32 v10, v10
	v_rcp_f32_e32 v2, v7
	s_nop 0
	v_mul_f32_e32 v2, v3, v2
	v_mul_f32_e32 v2, v32, v2
	v_add_f32_e32 v3, 1.0, v10
	v_cvt_pk_bf16_f32 v2, v2, s0
	ds_write_b16 v168, v2 offset:40992
	v_fma_f32 v9, v37, v167, v143
	v_fmac_f32_e32 v9, v38, v145
	v_fmac_f32_e32 v9, v39, v144
	v_mul_f32_e32 v7, 0xbfb8aa3b, v9
	v_exp_f32_e32 v7, v7
	v_rcp_f32_e32 v2, v3
	s_nop 0
	v_mul_f32_e32 v2, v6, v2
	v_mul_f32_e32 v2, v33, v2
	v_add_f32_e32 v3, 1.0, v7
	v_cvt_pk_bf16_f32 v2, v2, s0
	ds_write_b16 v168, v2 offset:41248
	v_mul_f32_e32 v6, 0xbfb8aa3b, v13
	v_exp_f32_e32 v6, v6
	v_rcp_f32_e32 v2, v3
	s_nop 0
	v_mul_f32_e32 v2, v9, v2
	v_mul_f32_e32 v2, v34, v2
	v_add_f32_e32 v3, 1.0, v6
; DEVI u16 f2bf(float f) { return (u16)(pack2(f, 0.f) & 0xffffu); }
; DEVI float bf2f(u16 h) { return __uint_as_float(((unsigned)h) << 16); }
; DEVI float siluf(float x) { return x / (1.f + __expf(-x)); }
; template <int MODE> ...
;     ...
;             for (int n = 0; n < 2; ++n) {
;               const int rowb = ai * HALF + ewr * 64 + m * 16 + efq * 4;
;               float gm = rowb > 0 ? bf2f(*(const u16*)(ls + gbase + ((ai * HALF + m * 16 - 1) * 256 + n * 32))) : 0.f;
;               float gp = rowb < 252 ? bf2f(*(const u16*)(ls + gbase + ((ai * HALF + m * 16 + 4) * 256 + n * 32))) : 0.f;
;               float g0 = acc[ai][0][m][n][0], g1 = acc[ai][0][m][n][1], g2 = acc[ai][0][m][n][2], g3 = acc[ai][0][m][n][3];
;               float z0 = cbb[n] + cw0[n] * gm + cw1[n] * g0 + cw2[n] * g1;
;               float z1 = cbb[n] + cw0[n] * g0 + cw1[n] * g1 + cw2[n] * g2;
;               float z2 = cbb[n] + cw0[n] * g1 + cw1[n] * g2 + cw2[n] * g3;
;               float z3 = cbb[n] + cw0[n] * g2 + cw1[n] * g3 + cw2[n] * gp;
;               char* hp = ls + hbase + ((ai * HALF + m * 16) * 256 + n * 32);
;               *(u16*)(hp) = f2bf(siluf(z0) * acc[ai][1][m][n][0]);
;               *(u16*)(hp + 256) = f2bf(siluf(z1) * acc[ai][1][m][n][1]);
;               *(u16*)(hp + 512) = f2bf(siluf(z2) * acc[ai][1][m][n][2]);
;               *(u16*)(hp + 768) = f2bf(siluf(z3) * acc[ai][1][m][n][3]);
;             }
;         {
;           float* sd = outf + (long)pm * 6 * DFF + colg;
;           if (ewr == 0 && efq == 0) {
; #pragma unroll
;             for (int n = 0; n < 2; ++n) {
;               sd[0 * DFF + n * 16] = acc[0][0][0][n][0]; sd[1 * DFF + n * 16] = acc[0][0][0][n][1]; sd[4 * DFF + n * 16] = acc[0][1][0][n][0];
;             }
	v_cvt_pk_bf16_f32 v2, v2, s0
	ds_write_b16 v168, v2 offset:41504
	v_cmp_lt_i32_e64 s[8:9], s82, v174
	v_rcp_f32_e32 v2, v3
	s_nop 0
	v_mul_f32_e32 v2, v13, v2
	v_mul_f32_e32 v2, v35, v2
	v_cvt_pk_bf16_f32 v2, v2, s0
	ds_write_b16 v168, v2 offset:41760
	v_mov_b32_e32 v2, 0
	v_mov_b32_e32 v3, 0
	v_lshlrev_b32_e32 v3, 16, v208
	v_cndmask_b32_e64 v3, 0, v3, s[8:9]
	v_cmp_gt_i32_e64 s[10:11], s83, v174
	v_lshlrev_b32_e32 v2, 16, v209
	s_nop 0
	v_cndmask_b32_e64 v2, 0, v2, s[10:11]
	v_fma_f32 v3, v171, v3, v170
	v_fmac_f32_e32 v3, v20, v172
	v_fmac_f32_e32 v3, v21, v173
	v_mul_f32_e32 v7, 0xbfb8aa3b, v3
	v_exp_f32_e32 v7, v7
	v_fma_f32 v6, v20, v171, v170
	v_fma_f32 v9, v21, v171, v170
	v_fmac_f32_e32 v170, v22, v171
	v_add_f32_e32 v7, 1.0, v7
	v_fmac_f32_e32 v170, v23, v172
	v_fmac_f32_e32 v170, v173, v2
	v_fmac_f32_e32 v6, v21, v172
	v_fmac_f32_e32 v6, v22, v173
	v_mul_f32_e32 v10, 0xbfb8aa3b, v6
	v_exp_f32_e32 v10, v10
	v_rcp_f32_e32 v2, v7
	s_nop 0
	v_mul_f32_e32 v2, v3, v2
	v_mul_f32_e32 v2, v28, v2
	v_add_f32_e32 v3, 1.0, v10
	v_cvt_pk_bf16_f32 v2, v2, s0
	ds_write_b16 v168, v2 offset:45056
	v_fmac_f32_e32 v9, v22, v172
	v_fmac_f32_e32 v9, v23, v173
	v_mul_f32_e32 v7, 0xbfb8aa3b, v9
	v_exp_f32_e32 v7, v7
	v_rcp_f32_e32 v2, v3
	s_nop 0
	v_mul_f32_e32 v2, v6, v2
	v_mul_f32_e32 v2, v29, v2
	v_add_f32_e32 v3, 1.0, v7
	v_cvt_pk_bf16_f32 v2, v2, s0
	ds_write_b16 v168, v2 offset:45312
	v_mul_f32_e32 v6, 0xbfb8aa3b, v170
	v_exp_f32_e32 v6, v6
	v_rcp_f32_e32 v2, v3
	s_nop 0
	v_mul_f32_e32 v2, v9, v2
	v_mul_f32_e32 v2, v30, v2
	v_add_f32_e32 v3, 1.0, v6
	v_cvt_pk_bf16_f32 v2, v2, s0
	ds_write_b16 v168, v2 offset:45568
	v_rcp_f32_e32 v2, v3
	s_nop 0
	v_mul_f32_e32 v2, v170, v2
	v_mul_f32_e32 v2, v31, v2
	v_cvt_pk_bf16_f32 v2, v2, s0
	ds_write_b16 v168, v2 offset:45824
	v_mov_b32_e32 v2, 0
	v_mov_b32_e32 v3, 0
	v_lshlrev_b32_e32 v3, 16, v210
	v_cndmask_b32_e64 v3, 0, v3, s[8:9]
	v_lshlrev_b32_e32 v2, 16, v211
	v_cndmask_b32_e64 v2, 0, v2, s[10:11]
	v_fma_f32 v3, v167, v3, v143
	v_fmac_f32_e32 v3, v16, v145
	v_fmac_f32_e32 v3, v17, v144
	v_mul_f32_e32 v7, 0xbfb8aa3b, v3
	v_exp_f32_e32 v7, v7
	v_fma_f32 v6, v16, v167, v143
	v_fma_f32 v9, v17, v167, v143
	v_fmac_f32_e32 v143, v18, v167
	v_add_f32_e32 v7, 1.0, v7
	v_fmac_f32_e32 v143, v19, v145
	v_fmac_f32_e32 v143, v144, v2
	v_fmac_f32_e32 v6, v17, v145
	v_fmac_f32_e32 v6, v18, v144
	v_mul_f32_e32 v10, 0xbfb8aa3b, v6
	v_exp_f32_e32 v10, v10
	v_rcp_f32_e32 v2, v7
	s_nop 0
	v_mul_f32_e32 v2, v3, v2
	v_mul_f32_e32 v2, v24, v2
	v_add_f32_e32 v3, 1.0, v10
	v_cvt_pk_bf16_f32 v2, v2, s0
	ds_write_b16 v168, v2 offset:45088
	v_fmac_f32_e32 v9, v18, v145
	v_fmac_f32_e32 v9, v19, v144
	v_mul_f32_e32 v7, 0xbfb8aa3b, v9
	v_exp_f32_e32 v7, v7
	v_rcp_f32_e32 v2, v3
	s_nop 0
	v_mul_f32_e32 v2, v6, v2
	v_mul_f32_e32 v2, v25, v2
	v_add_f32_e32 v3, 1.0, v7
	v_cvt_pk_bf16_f32 v2, v2, s0
	ds_write_b16 v168, v2 offset:45344
	v_mul_f32_e32 v6, 0xbfb8aa3b, v143
	v_exp_f32_e32 v6, v6
	v_rcp_f32_e32 v2, v3
	s_nop 0
	v_mul_f32_e32 v2, v9, v2
	v_mul_f32_e32 v2, v26, v2
	v_add_f32_e32 v3, 1.0, v6
	v_cvt_pk_bf16_f32 v2, v2, s0
	ds_write_b16 v168, v2 offset:45600
	s_mul_i32 s8, s86, 6
	v_rcp_f32_e32 v2, v3
	s_nop 0
	v_mul_f32_e32 v2, v143, v2
	s_mul_i32 s86, s86, 0x40800
	v_mul_f32_e32 v2, v27, v2
	s_mul_hi_i32 s9, s8, 0xac00
	s_add_u32 s8, s33, s86
	v_cvt_pk_bf16_f32 v2, v2, s0
	s_addc_u32 s9, s70, s9
	ds_write_b16 v168, v2 offset:45856
	v_lshl_add_u64 v[2:3], v[138:139], 2, s[8:9]
	v_cmp_gt_u32_e32 vcc, s71, v140
	v_cmp_eq_u32_e64 s[8:9], 0, v142
	s_and_b64 s[10:11], vcc, s[8:9]
	s_and_saveexec_b64 s[8:9], s[10:11]
	s_cbranch_execz .LBB0_660
	v_add_co_u32_e32 v6, vcc, 0xa000, v2
	global_store_dword v[2:3], v4, off
	s_nop 0
	v_addc_co_u32_e32 v7, vcc, 0, v3, vcc
	v_add_co_u32_e32 v4, vcc, 0x2b000, v2
	global_store_dword v[6:7], v5, off offset:3072
	s_nop 0
	v_addc_co_u32_e32 v5, vcc, 0, v3, vcc
	global_store_dword v[4:5], v12, off
	global_store_dword v[2:3], v0, off offset:64
	global_store_dword v[6:7], v1, off offset:3136
	global_store_dword v[4:5], v8, off offset:64
